# MLA loop: V-tile LDS-DMA issued at the end of the QK section (after the V-fragment reads) instead of after the seventh QK MFMA
# speedup vs baseline: 1.0022x; 1.0022x over previous
.LBB0_352:
	s_waitcnt lgkmcnt(1)
	v_mfma_f32_32x32x16_bf16 v[2:17], v[18:21], v[116:119], v[96:111]
	s_waitcnt lgkmcnt(0)
	v_mfma_f32_32x32x16_bf16 v[64:79], v[22:25], v[116:119], v[96:111]
	ds_read_b128 v[18:21], v84 offset:2048
	ds_read_b128 v[22:25], v84 offset:2560
	s_waitcnt lgkmcnt(0)
	v_mfma_f32_32x32x16_bf16 v[64:79], v[22:25], v[120:123], v[64:79]
	v_mfma_f32_32x32x16_bf16 v[2:17], v[18:21], v[120:123], v[2:17]
	ds_read_b128 v[18:21], v84 offset:4096
	ds_read_b128 v[22:25], v84 offset:4608
	s_waitcnt lgkmcnt(0)
	v_mfma_f32_32x32x16_bf16 v[64:79], v[22:25], v[124:127], v[64:79]
	v_mfma_f32_32x32x16_bf16 v[2:17], v[18:21], v[124:127], v[2:17]
	ds_read_b128 v[18:21], v84 offset:6144
	ds_read_b128 v[22:25], v84 offset:6656
	s_waitcnt lgkmcnt(0)
	v_mfma_f32_32x32x16_bf16 v[64:79], v[22:25], v[128:131], v[64:79]
	ds_read_b128 v[22:25], v84 offset:8704
	ds_read_b128 v[26:29], v84 offset:10240
	v_add_u32_e32 v115, s0, v196
	v_mfma_f32_32x32x16_bf16 v[2:17], v[18:21], v[128:131], v[2:17]
	ds_read_b128 v[18:21], v84 offset:8192
	s_waitcnt lgkmcnt(0)
	v_mfma_f32_32x32x16_bf16 v[2:17], v[18:21], v[132:135], v[2:17]
	ds_read_b64_tr_b16 v[152:153], v115 offset:12288
	ds_read_b64_tr_b16 v[154:155], v115 offset:12800
	ds_read_b64_tr_b16 v[88:89], v115 offset:13312
	ds_read_b64_tr_b16 v[90:91], v115 offset:13824
	ds_read_b64_tr_b16 v[80:81], v115 offset:14336
	ds_read_b64_tr_b16 v[82:83], v115 offset:14848
	ds_read_b64_tr_b16 v[18:19], v115 offset:15360
	ds_read_b64_tr_b16 v[20:21], v115 offset:15872
	ds_read_b128 v[200:203], v84 offset:10752
	v_mfma_f32_32x32x16_bf16 v[64:79], v[22:25], v[132:135], v[64:79]
	v_mfma_f32_32x32x16_bf16 v[2:17], v[26:29], v[136:139], v[2:17]
	ds_read_b64_tr_b16 v[92:93], v115 offset:16384
	ds_read_b64_tr_b16 v[94:95], v115 offset:16896
	ds_read_b64_tr_b16 v[84:85], v115 offset:17408
	ds_read_b64_tr_b16 v[86:87], v115 offset:17920
	ds_read_b64_tr_b16 v[26:27], v115 offset:18432
	ds_read_b64_tr_b16 v[28:29], v115 offset:18944
	ds_read_b64_tr_b16 v[22:23], v115 offset:19456
	ds_read_b64_tr_b16 v[24:25], v115 offset:19968
	v_ashrrev_i32_e32 v205, 31, v114
	v_mov_b32_e32 v204, v114
	s_add_i32 m0, s101, 0x2f80
	v_lshlrev_b64 v[204:205], 11, v[204:205]
	v_lshl_add_u64 v[204:205], v[30:31], 0, v[204:205]
	global_load_lds_dwordx4 v[204:205], off offset:128
	s_waitcnt lgkmcnt(8)
	v_mfma_f32_32x32x16_bf16 v[64:79], v[200:203], v[136:139], v[64:79]
	v_max3_f32 v115, v2, v3, v64
	v_max3_f32 v171, v4, v5, v65
	v_max3_f32 v115, v115, v66, v67
	v_max3_f32 v171, v171, v8, v9
	v_max3_f32 v115, v115, v6, v7
	v_max3_f32 v171, v171, v70, v71
	v_max3_f32 v115, v115, v68, v69
	v_max3_f32 v171, v171, v12, v13
	v_max3_f32 v115, v115, v10, v11
	v_max3_f32 v171, v171, v74, v75
	v_max3_f32 v115, v115, v72, v73
	v_max3_f32 v171, v171, v16, v17
	v_max3_f32 v115, v115, v14, v15
	v_max3_f32 v171, v171, v78, v79
	v_max3_f32 v115, v115, v76, v77
	v_max_f32_e32 v115, v115, v171
	v_mov_b32_e32 v171, v115
	s_nop 1
	v_permlane32_swap_b32_e32 v115, v171
	v_max_f32_e32 v115, v115, v171
	v_cmp_lt_f32_e32 vcc, s75, v115
	s_cbranch_vccz .LBB0_356
	v_max_f32_e32 v96, v115, v115
	v_max_f32_e32 v98, 0, v96
	v_exp_f32_e64 v115, -v98
	s_and_saveexec_b64 s[0:1], s[40:41]
	ds_write_b32 v198, v115 offset:41472
	s_or_b64 exec, exec, s[0:1]
	s_waitcnt lgkmcnt(0)
	ds_read_b128 v[200:203], v1 offset:41472
	ds_read_b128 v[204:207], v1 offset:41504
	ds_read_b128 v[208:211], v1 offset:41536
	ds_read_b128 v[212:215], v1 offset:41568
	v_add_f32_e32 v0, v0, v98
	s_waitcnt lgkmcnt(0)
	v_xor_b32_e32 v96, 0x80000000, v0
	v_pk_add_f32 v[2:3], v[2:3], v[98:99] op_sel_hi:[1,0] neg_lo:[0,1] neg_hi:[0,1]
	v_pk_add_f32 v[64:65], v[64:65], v[98:99] op_sel_hi:[1,0] neg_lo:[0,1] neg_hi:[0,1]
	v_pk_add_f32 v[4:5], v[4:5], v[98:99] op_sel_hi:[1,0] neg_lo:[0,1] neg_hi:[0,1]
	v_pk_add_f32 v[66:67], v[66:67], v[98:99] op_sel_hi:[1,0] neg_lo:[0,1] neg_hi:[0,1]
	v_pk_add_f32 v[6:7], v[6:7], v[98:99] op_sel_hi:[1,0] neg_lo:[0,1] neg_hi:[0,1]
	v_pk_add_f32 v[68:69], v[68:69], v[98:99] op_sel_hi:[1,0] neg_lo:[0,1] neg_hi:[0,1]
	v_pk_add_f32 v[8:9], v[8:9], v[98:99] op_sel_hi:[1,0] neg_lo:[0,1] neg_hi:[0,1]
	v_pk_add_f32 v[70:71], v[70:71], v[98:99] op_sel_hi:[1,0] neg_lo:[0,1] neg_hi:[0,1]
	v_pk_add_f32 v[10:11], v[10:11], v[98:99] op_sel_hi:[1,0] neg_lo:[0,1] neg_hi:[0,1]
	v_pk_add_f32 v[72:73], v[72:73], v[98:99] op_sel_hi:[1,0] neg_lo:[0,1] neg_hi:[0,1]
	v_pk_add_f32 v[12:13], v[12:13], v[98:99] op_sel_hi:[1,0] neg_lo:[0,1] neg_hi:[0,1]
	v_pk_add_f32 v[74:75], v[74:75], v[98:99] op_sel_hi:[1,0] neg_lo:[0,1] neg_hi:[0,1]
	v_pk_add_f32 v[14:15], v[14:15], v[98:99] op_sel_hi:[1,0] neg_lo:[0,1] neg_hi:[0,1]
	v_pk_add_f32 v[76:77], v[76:77], v[98:99] op_sel_hi:[1,0] neg_lo:[0,1] neg_hi:[0,1]
	v_pk_add_f32 v[16:17], v[16:17], v[98:99] op_sel_hi:[1,0] neg_lo:[0,1] neg_hi:[0,1]
	v_pk_add_f32 v[78:79], v[78:79], v[98:99] op_sel_hi:[1,0] neg_lo:[0,1] neg_hi:[0,1]
	v_mov_b32_e32 v97, v96
	v_mov_b32_e32 v98, v96
	v_mov_b32_e32 v99, v96
	v_mov_b32_e32 v100, v96
	v_mov_b32_e32 v101, v96
	v_mov_b32_e32 v102, v96
	v_mov_b32_e32 v103, v96
	v_mov_b32_e32 v104, v96
	v_mov_b32_e32 v105, v96
	v_mov_b32_e32 v106, v96
	v_mov_b32_e32 v107, v96
	v_mov_b32_e32 v108, v96
	v_mov_b32_e32 v109, v96
	v_mov_b32_e32 v110, v96
	v_mov_b32_e32 v111, v96
	v_mul_f32_e32 v163, v163, v115
	s_waitcnt lgkmcnt(0)
	v_pk_mul_f32 v[46:47], v[46:47], v[214:215]
	v_pk_mul_f32 v[42:43], v[42:43], v[210:211]
	v_pk_mul_f32 v[38:39], v[38:39], v[206:207]
	v_pk_mul_f32 v[34:35], v[34:35], v[202:203]
	v_pk_mul_f32 v[44:45], v[44:45], v[212:213]
	v_pk_mul_f32 v[40:41], v[40:41], v[208:209]
	v_pk_mul_f32 v[36:37], v[36:37], v[204:205]
	v_pk_mul_f32 v[32:33], v[32:33], v[200:201]
	v_pk_mul_f32 v[62:63], v[62:63], v[214:215]
	v_pk_mul_f32 v[58:59], v[58:59], v[210:211]
	v_pk_mul_f32 v[54:55], v[54:55], v[206:207]
	v_pk_mul_f32 v[50:51], v[50:51], v[202:203]
	v_pk_mul_f32 v[60:61], v[60:61], v[212:213]
	v_pk_mul_f32 v[56:57], v[56:57], v[208:209]
	v_pk_mul_f32 v[52:53], v[52:53], v[204:205]
	v_pk_mul_f32 v[48:49], v[48:49], v[200:201]
